# no accumulator clearing in GEMM1/GEMM3/FF1: first K-loop iteration peeled, first MFMA per accumulator takes srcC=0
# speedup vs baseline: 1.0130x; 1.0087x over previous
.LBB0_227:
	s_ashr_i32 s69, s68, 31
	s_lshl_b64 s[10:11], s[68:69], 19
	s_add_u32 s72, s52, s10
	s_addc_u32 s73, s53, s11
	s_and_b64 s[10:11], s[4:5], exec
	s_cselect_b32 s18, s73, s7
	s_cselect_b32 s69, s72, s6
	s_ashr_i32 s71, s70, 31
	s_lshl_b64 s[10:11], s[70:71], 19
	s_add_u32 s74, s59, s10
	s_addc_u32 s75, s67, s11
	s_and_b64 s[10:11], s[4:5], exec
	s_cselect_b32 s71, s75, s9
	s_cselect_b32 s77, s74, s8
	s_add_u32 vcc_lo, s8, 0x100
	s_addc_u32 vcc_hi, s9, 0
	s_mov_b32 s92, -2
	ds_read_b128 v[128:131], v179
	ds_read_b128 v[132:135], v179 offset:1024
	ds_read_b128 v[136:139], v179 offset:2048
	ds_read_b128 v[140:143], v179 offset:3072
	ds_read_b128 v[162:165], v180
	ds_read_b128 v[166:169], v180 offset:1024
	ds_read_b128 v[170:173], v180 offset:2048
	ds_read_b128 v[186:189], v180 offset:3072
	s_add_u32 s8, s6, 0x10000
	s_addc_u32 s9, s7, 0
	s_cmp_eq_u32 s92, 12
	s_cselect_b32 s80, s69, s8
	s_cselect_b32 s81, s18, s9
	s_cselect_b32 s12, s77, vcc_lo
	s_cselect_b32 s13, s71, vcc_hi
	s_add_u32 s10, s80, 0x8000
	s_addc_u32 s11, s81, 0
	s_add_i32 m0, s79, 0xc000
	ds_read_b128 v[190:193], v181
	ds_read_b128 v[194:197], v181 offset:1024
	ds_read_b128 v[198:201], v181 offset:2048
	ds_read_b128 v[202:205], v181 offset:3072
	ds_read_b128 v[206:209], v181 offset:4096
	ds_read_b128 v[210:213], v181 offset:5120
	ds_read_b128 v[214:217], v181 offset:6144
	ds_read_b128 v[218:221], v181 offset:7168
	global_load_lds_dwordx4 v154, s[6:7]
	s_add_i32 m0, s79, 0xe000
	s_nop 0
	global_load_lds_dwordx4 v156, s[6:7]
	s_waitcnt vmcnt(8)
	s_waitcnt lgkmcnt(0)
	s_setprio 1
	s_barrier
	v_mfma_f32_16x16x32_bf16 v[124:127], v[128:131], v[190:193], 0
	v_mfma_f32_16x16x32_bf16 v[120:123], v[136:139], v[190:193], 0
	v_mfma_f32_16x16x32_bf16 v[108:111], v[128:131], v[198:201], 0
	v_mfma_f32_16x16x32_bf16 v[104:107], v[136:139], v[198:201], 0
	v_mfma_f32_16x16x32_bf16 v[92:95], v[128:131], v[206:209], 0
	v_mfma_f32_16x16x32_bf16 v[88:91], v[136:139], v[206:209], 0
	v_mfma_f32_16x16x32_bf16 v[76:79], v[128:131], v[214:217], 0
	v_mfma_f32_16x16x32_bf16 v[72:75], v[136:139], v[214:217], 0
	v_mfma_f32_16x16x32_bf16 v[124:127], v[132:135], v[194:197], v[124:127]
	v_mfma_f32_16x16x32_bf16 v[120:123], v[140:143], v[194:197], v[120:123]
	v_mfma_f32_16x16x32_bf16 v[108:111], v[132:135], v[202:205], v[108:111]
	v_mfma_f32_16x16x32_bf16 v[104:107], v[140:143], v[202:205], v[104:107]
	v_mfma_f32_16x16x32_bf16 v[92:95], v[132:135], v[210:213], v[92:95]
	v_mfma_f32_16x16x32_bf16 v[88:91], v[140:143], v[210:213], v[88:91]
	v_mfma_f32_16x16x32_bf16 v[76:79], v[132:135], v[218:221], v[76:79]
	v_mfma_f32_16x16x32_bf16 v[72:75], v[140:143], v[218:221], v[72:75]
	v_mfma_f32_16x16x32_bf16 v[116:119], v[162:165], v[190:193], 0
	v_mfma_f32_16x16x32_bf16 v[112:115], v[170:173], v[190:193], 0
	v_mfma_f32_16x16x32_bf16 v[100:103], v[162:165], v[198:201], 0
	v_mfma_f32_16x16x32_bf16 v[96:99], v[170:173], v[198:201], 0
	v_mfma_f32_16x16x32_bf16 v[84:87], v[162:165], v[206:209], 0
	v_mfma_f32_16x16x32_bf16 v[80:83], v[170:173], v[206:209], 0
	v_mfma_f32_16x16x32_bf16 v[68:71], v[162:165], v[214:217], 0
	v_mfma_f32_16x16x32_bf16 v[64:67], v[170:173], v[214:217], 0
	v_mfma_f32_16x16x32_bf16 v[116:119], v[166:169], v[194:197], v[116:119]
	v_mfma_f32_16x16x32_bf16 v[112:115], v[186:189], v[194:197], v[112:115]
	v_mfma_f32_16x16x32_bf16 v[100:103], v[166:169], v[202:205], v[100:103]
	v_mfma_f32_16x16x32_bf16 v[96:99], v[186:189], v[202:205], v[96:99]
	v_mfma_f32_16x16x32_bf16 v[84:87], v[166:169], v[210:213], v[84:87]
	v_mfma_f32_16x16x32_bf16 v[80:83], v[186:189], v[210:213], v[80:83]
	v_mfma_f32_16x16x32_bf16 v[68:71], v[166:169], v[218:221], v[68:71]
	v_mfma_f32_16x16x32_bf16 v[64:67], v[186:189], v[218:221], v[64:67]
	s_barrier
	s_setprio 0
	s_add_i32 s6, s34, s84
	s_mov_b32 m0, s6
	ds_read_b128 v[190:193], v181 offset:16384
	ds_read_b128 v[194:197], v181 offset:17408
	ds_read_b128 v[198:201], v181 offset:18432
	ds_read_b128 v[202:205], v181 offset:19456
	ds_read_b128 v[206:209], v181 offset:20480
	ds_read_b128 v[210:213], v181 offset:21504
	ds_read_b128 v[214:217], v181 offset:22528
	ds_read_b128 v[218:221], v181 offset:23552
	global_load_lds_dwordx4 v146, s[12:13]
	s_add_i32 m0, s6, 0x2000
	s_add_u32 s6, s12, 0x40000
	s_addc_u32 s7, s13, 0
	s_add_i32 s38, s35, s84
	global_load_lds_dwordx4 v150, s[12:13]
	s_mov_b32 m0, s38
	s_nop 0
	global_load_lds_dwordx4 v146, s[6:7]
	s_add_i32 m0, s38, 0x2000
	s_nop 0
	global_load_lds_dwordx4 v150, s[6:7]
	s_mov_b32 m0, s79
	s_nop 0
	global_load_lds_dwordx4 v144, s[80:81]
	s_mov_b32 m0, s85
	s_nop 0
	global_load_lds_dwordx4 v148, s[80:81]
	s_waitcnt vmcnt(8)
	s_waitcnt lgkmcnt(0)
	s_setprio 1
	s_barrier
	v_mfma_f32_16x16x32_bf16 v[60:63], v[128:131], v[190:193], 0
	v_mfma_f32_16x16x32_bf16 v[56:59], v[136:139], v[190:193], 0
	v_mfma_f32_16x16x32_bf16 v[44:47], v[128:131], v[198:201], 0
	v_mfma_f32_16x16x32_bf16 v[40:43], v[136:139], v[198:201], 0
	v_mfma_f32_16x16x32_bf16 v[28:31], v[128:131], v[206:209], 0
	v_mfma_f32_16x16x32_bf16 v[24:27], v[136:139], v[206:209], 0
	v_mfma_f32_16x16x32_bf16 v[12:15], v[128:131], v[214:217], 0
	v_mfma_f32_16x16x32_bf16 v[8:11], v[136:139], v[214:217], 0
	v_mfma_f32_16x16x32_bf16 v[60:63], v[132:135], v[194:197], v[60:63]
	v_mfma_f32_16x16x32_bf16 v[56:59], v[140:143], v[194:197], v[56:59]
	v_mfma_f32_16x16x32_bf16 v[44:47], v[132:135], v[202:205], v[44:47]
	v_mfma_f32_16x16x32_bf16 v[40:43], v[140:143], v[202:205], v[40:43]
	v_mfma_f32_16x16x32_bf16 v[28:31], v[132:135], v[210:213], v[28:31]
	v_mfma_f32_16x16x32_bf16 v[24:27], v[140:143], v[210:213], v[24:27]
	v_mfma_f32_16x16x32_bf16 v[12:15], v[132:135], v[218:221], v[12:15]
	v_mfma_f32_16x16x32_bf16 v[8:11], v[140:143], v[218:221], v[8:11]
	v_mfma_f32_16x16x32_bf16 v[52:55], v[162:165], v[190:193], 0
	v_mfma_f32_16x16x32_bf16 v[48:51], v[170:173], v[190:193], 0
	v_mfma_f32_16x16x32_bf16 v[36:39], v[162:165], v[198:201], 0
	v_mfma_f32_16x16x32_bf16 v[32:35], v[170:173], v[198:201], 0
	v_mfma_f32_16x16x32_bf16 v[20:23], v[162:165], v[206:209], 0
	v_mfma_f32_16x16x32_bf16 v[16:19], v[170:173], v[206:209], 0
	v_mfma_f32_16x16x32_bf16 v[4:7], v[162:165], v[214:217], 0
	v_mfma_f32_16x16x32_bf16 v[0:3], v[170:173], v[214:217], 0
	v_mfma_f32_16x16x32_bf16 v[52:55], v[166:169], v[194:197], v[52:55]
	v_mfma_f32_16x16x32_bf16 v[48:51], v[186:189], v[194:197], v[48:51]
	v_mfma_f32_16x16x32_bf16 v[36:39], v[166:169], v[202:205], v[36:39]
	v_mfma_f32_16x16x32_bf16 v[32:35], v[186:189], v[202:205], v[32:35]
	v_mfma_f32_16x16x32_bf16 v[20:23], v[166:169], v[210:213], v[20:23]
	v_mfma_f32_16x16x32_bf16 v[16:19], v[186:189], v[210:213], v[16:19]
	v_mfma_f32_16x16x32_bf16 v[4:7], v[166:169], v[218:221], v[4:7]
	v_mfma_f32_16x16x32_bf16 v[0:3], v[186:189], v[218:221], v[0:3]
	s_barrier
	s_setprio 0
	s_add_i32 s38, 0, 0x18000
	s_add_i32 s39, 0, 0x1c000
	v_add_u32_e32 v140, s38, v178
	v_add_u32_e32 v152, s39, v178
	ds_read_b128 v[128:131], v140
	ds_read_b128 v[132:135], v140 offset:1024
	ds_read_b128 v[136:139], v140 offset:2048
	ds_read_b128 v[140:143], v140 offset:3072
	ds_read_b128 v[162:165], v152
	ds_read_b128 v[166:169], v152 offset:1024
	ds_read_b128 v[170:173], v152 offset:2048
	ds_read_b128 v[186:189], v152 offset:3072
	s_add_u32 s6, s80, 0x4000
	s_addc_u32 s7, s81, 0
	s_mov_b32 m0, s86
	ds_read_b128 v[190:193], v181 offset:32768
	ds_read_b128 v[194:197], v181 offset:33792
	ds_read_b128 v[198:201], v181 offset:34816
	ds_read_b128 v[202:205], v181 offset:35840
	ds_read_b128 v[206:209], v181 offset:36864
	ds_read_b128 v[210:213], v181 offset:37888
	ds_read_b128 v[214:217], v181 offset:38912
	ds_read_b128 v[218:221], v181 offset:39936
	global_load_lds_dwordx4 v144, s[6:7]
	s_mov_b32 m0, s87
	s_nop 0
	global_load_lds_dwordx4 v148, s[6:7]
	s_waitcnt vmcnt(8)
	s_waitcnt lgkmcnt(0)
	s_setprio 1
	s_barrier
	v_mfma_f32_16x16x32_bf16 v[124:127], v[128:131], v[190:193], v[124:127]
	v_mfma_f32_16x16x32_bf16 v[120:123], v[136:139], v[190:193], v[120:123]
	v_mfma_f32_16x16x32_bf16 v[108:111], v[128:131], v[198:201], v[108:111]
	v_mfma_f32_16x16x32_bf16 v[104:107], v[136:139], v[198:201], v[104:107]
	v_mfma_f32_16x16x32_bf16 v[92:95], v[128:131], v[206:209], v[92:95]
	v_mfma_f32_16x16x32_bf16 v[88:91], v[136:139], v[206:209], v[88:91]
	v_mfma_f32_16x16x32_bf16 v[76:79], v[128:131], v[214:217], v[76:79]
	v_mfma_f32_16x16x32_bf16 v[72:75], v[136:139], v[214:217], v[72:75]
	v_mfma_f32_16x16x32_bf16 v[124:127], v[132:135], v[194:197], v[124:127]
	v_mfma_f32_16x16x32_bf16 v[120:123], v[140:143], v[194:197], v[120:123]
	v_mfma_f32_16x16x32_bf16 v[108:111], v[132:135], v[202:205], v[108:111]
	v_mfma_f32_16x16x32_bf16 v[104:107], v[140:143], v[202:205], v[104:107]
	v_mfma_f32_16x16x32_bf16 v[92:95], v[132:135], v[210:213], v[92:95]
	v_mfma_f32_16x16x32_bf16 v[88:91], v[140:143], v[210:213], v[88:91]
	v_mfma_f32_16x16x32_bf16 v[76:79], v[132:135], v[218:221], v[76:79]
	v_mfma_f32_16x16x32_bf16 v[72:75], v[140:143], v[218:221], v[72:75]
	v_mfma_f32_16x16x32_bf16 v[116:119], v[162:165], v[190:193], v[116:119]
	v_mfma_f32_16x16x32_bf16 v[112:115], v[170:173], v[190:193], v[112:115]
	v_mfma_f32_16x16x32_bf16 v[100:103], v[162:165], v[198:201], v[100:103]
	v_mfma_f32_16x16x32_bf16 v[96:99], v[170:173], v[198:201], v[96:99]
	v_mfma_f32_16x16x32_bf16 v[84:87], v[162:165], v[206:209], v[84:87]
	v_mfma_f32_16x16x32_bf16 v[80:83], v[170:173], v[206:209], v[80:83]
	v_mfma_f32_16x16x32_bf16 v[68:71], v[162:165], v[214:217], v[68:71]
	v_mfma_f32_16x16x32_bf16 v[64:67], v[170:173], v[214:217], v[64:67]
	v_mfma_f32_16x16x32_bf16 v[116:119], v[166:169], v[194:197], v[116:119]
	v_mfma_f32_16x16x32_bf16 v[112:115], v[186:189], v[194:197], v[112:115]
	v_mfma_f32_16x16x32_bf16 v[100:103], v[166:169], v[202:205], v[100:103]
	v_mfma_f32_16x16x32_bf16 v[96:99], v[186:189], v[202:205], v[96:99]
	v_mfma_f32_16x16x32_bf16 v[84:87], v[166:169], v[210:213], v[84:87]
	v_mfma_f32_16x16x32_bf16 v[80:83], v[186:189], v[210:213], v[80:83]
	v_mfma_f32_16x16x32_bf16 v[68:71], v[166:169], v[218:221], v[68:71]
	v_mfma_f32_16x16x32_bf16 v[64:67], v[186:189], v[218:221], v[64:67]
	s_barrier
	s_setprio 0
	s_add_u32 s98, s12, s48
	s_addc_u32 s99, s13, s49
	s_add_i32 s6, s38, s84
	s_mov_b32 m0, s6
	ds_read_b128 v[190:193], v181 offset:49152
	ds_read_b128 v[194:197], v181 offset:50176
	ds_read_b128 v[198:201], v181 offset:51200
	ds_read_b128 v[202:205], v181 offset:52224
	ds_read_b128 v[206:209], v181 offset:53248
	ds_read_b128 v[210:213], v181 offset:54272
	ds_read_b128 v[214:217], v181 offset:55296
	ds_read_b128 v[218:221], v181 offset:56320
	global_load_lds_dwordx4 v146, s[98:99]
	s_add_i32 m0, s6, 0x2000
	s_add_u32 s6, s12, 0x40080
	s_addc_u32 s7, s13, 0
	s_add_i32 s12, s39, s84
	global_load_lds_dwordx4 v150, s[98:99]
	s_mov_b32 m0, s12
	s_nop 0
	global_load_lds_dwordx4 v146, s[6:7]
	s_add_i32 m0, s12, 0x2000
	s_nop 0
	global_load_lds_dwordx4 v150, s[6:7]
	s_mov_b32 m0, s33
	s_nop 0
	global_load_lds_dwordx4 v144, s[10:11]
	s_mov_b32 m0, s56
	s_nop 0
	global_load_lds_dwordx4 v148, s[10:11]
	s_waitcnt vmcnt(8)
	s_waitcnt lgkmcnt(0)
	s_setprio 1
	s_barrier
	v_mfma_f32_16x16x32_bf16 v[60:63], v[128:131], v[190:193], v[60:63]
	v_mfma_f32_16x16x32_bf16 v[56:59], v[136:139], v[190:193], v[56:59]
	v_mfma_f32_16x16x32_bf16 v[44:47], v[128:131], v[198:201], v[44:47]
	v_mfma_f32_16x16x32_bf16 v[40:43], v[136:139], v[198:201], v[40:43]
	v_mfma_f32_16x16x32_bf16 v[28:31], v[128:131], v[206:209], v[28:31]
	v_mfma_f32_16x16x32_bf16 v[24:27], v[136:139], v[206:209], v[24:27]
	v_mfma_f32_16x16x32_bf16 v[12:15], v[128:131], v[214:217], v[12:15]
	v_mfma_f32_16x16x32_bf16 v[8:11], v[136:139], v[214:217], v[8:11]
	v_mfma_f32_16x16x32_bf16 v[60:63], v[132:135], v[194:197], v[60:63]
	v_mfma_f32_16x16x32_bf16 v[56:59], v[140:143], v[194:197], v[56:59]
	v_mfma_f32_16x16x32_bf16 v[44:47], v[132:135], v[202:205], v[44:47]
	v_mfma_f32_16x16x32_bf16 v[40:43], v[140:143], v[202:205], v[40:43]
	v_mfma_f32_16x16x32_bf16 v[28:31], v[132:135], v[210:213], v[28:31]
	v_mfma_f32_16x16x32_bf16 v[24:27], v[140:143], v[210:213], v[24:27]
	v_mfma_f32_16x16x32_bf16 v[12:15], v[132:135], v[218:221], v[12:15]
	v_mfma_f32_16x16x32_bf16 v[8:11], v[140:143], v[218:221], v[8:11]
	v_mfma_f32_16x16x32_bf16 v[52:55], v[162:165], v[190:193], v[52:55]
	v_mfma_f32_16x16x32_bf16 v[48:51], v[170:173], v[190:193], v[48:51]
	v_mfma_f32_16x16x32_bf16 v[36:39], v[162:165], v[198:201], v[36:39]
	v_mfma_f32_16x16x32_bf16 v[32:35], v[170:173], v[198:201], v[32:35]
	v_mfma_f32_16x16x32_bf16 v[20:23], v[162:165], v[206:209], v[20:23]
	v_mfma_f32_16x16x32_bf16 v[16:19], v[170:173], v[206:209], v[16:19]
	v_mfma_f32_16x16x32_bf16 v[4:7], v[162:165], v[214:217], v[4:7]
	v_mfma_f32_16x16x32_bf16 v[0:3], v[170:173], v[214:217], v[0:3]
	v_mfma_f32_16x16x32_bf16 v[52:55], v[166:169], v[194:197], v[52:55]
	v_mfma_f32_16x16x32_bf16 v[48:51], v[186:189], v[194:197], v[48:51]
	v_mfma_f32_16x16x32_bf16 v[36:39], v[166:169], v[202:205], v[36:39]
	v_mfma_f32_16x16x32_bf16 v[32:35], v[186:189], v[202:205], v[32:35]
	v_mfma_f32_16x16x32_bf16 v[20:23], v[166:169], v[210:213], v[20:23]
	v_mfma_f32_16x16x32_bf16 v[16:19], v[186:189], v[210:213], v[16:19]
	v_mfma_f32_16x16x32_bf16 v[4:7], v[166:169], v[218:221], v[4:7]
	v_mfma_f32_16x16x32_bf16 v[0:3], v[186:189], v[218:221], v[0:3]
	s_barrier
	s_setprio 0
	s_add_i32 s92, s92, 2
	s_add_u32 vcc_lo, vcc_lo, 0x100
	s_addc_u32 vcc_hi, vcc_hi, 0
	s_cmp_gt_u32 s92, 13
	s_mov_b64 s[6:7], s[8:9]

.LBB0_506:
	s_ashr_i32 s29, s28, 31
	v_cmp_lt_i64_e32 vcc, s[38:39], v[204:205]
	s_lshl_b64 s[38:39], s[28:29], 19
	s_add_u32 s38, s14, s38
	s_addc_u32 s39, s15, s39
	s_and_b64 s[40:41], vcc, exec
	s_cselect_b32 s8, s39, s43
	s_cselect_b32 s21, s38, s42
	s_ashr_i32 s27, s26, 31
	s_lshl_b64 s[40:41], s[26:27], 19
	s_add_u32 s40, s33, s40
	s_addc_u32 s41, s34, s41
	s_and_b64 s[46:47], vcc, exec
	s_cselect_b32 s27, s41, s45
	s_cselect_b32 s29, s40, s44
	s_add_u32 s80, s44, 0x100
	s_addc_u32 s81, s45, 0
	s_mov_b32 s83, -2
	ds_read_b128 v[128:131], v229
	ds_read_b128 v[132:135], v229 offset:1024
	ds_read_b128 v[136:139], v229 offset:2048
	ds_read_b128 v[140:143], v229 offset:3072
	ds_read_b128 v[144:147], v230
	ds_read_b128 v[148:151], v230 offset:1024
	ds_read_b128 v[152:155], v230 offset:2048
	ds_read_b128 v[156:159], v230 offset:3072
	s_add_u32 s44, s42, 0x10000
	s_addc_u32 s45, s43, 0
	s_cmp_eq_u32 s83, 12
	s_cselect_b32 s50, s21, s44
	s_cselect_b32 s51, s8, s45
	s_cselect_b32 s48, s29, s80
	s_cselect_b32 s49, s27, s81
	s_add_u32 s46, s50, 0x8000
	s_addc_u32 s47, s51, 0
	s_add_i32 m0, s23, 0xc000
	ds_read_b128 v[160:163], v231
	ds_read_b128 v[164:167], v231 offset:1024
	ds_read_b128 v[168:171], v231 offset:2048
	ds_read_b128 v[172:175], v231 offset:3072
	ds_read_b128 v[176:179], v231 offset:4096
	ds_read_b128 v[180:183], v231 offset:5120
	ds_read_b128 v[184:187], v231 offset:6144
	ds_read_b128 v[188:191], v231 offset:7168
	global_load_lds_dwordx4 v200, s[42:43]
	s_add_i32 m0, s23, 0xe000
	s_nop 0
	global_load_lds_dwordx4 v202, s[42:43]
	s_waitcnt vmcnt(8)
	s_waitcnt lgkmcnt(0)
	s_setprio 1
	s_barrier
	v_mfma_f32_16x16x32_bf16 v[124:127], v[128:131], v[160:163], 0
	v_mfma_f32_16x16x32_bf16 v[120:123], v[136:139], v[160:163], 0
	v_mfma_f32_16x16x32_bf16 v[108:111], v[128:131], v[168:171], 0
	v_mfma_f32_16x16x32_bf16 v[104:107], v[136:139], v[168:171], 0
	v_mfma_f32_16x16x32_bf16 v[92:95], v[128:131], v[176:179], 0
	v_mfma_f32_16x16x32_bf16 v[88:91], v[136:139], v[176:179], 0
	v_mfma_f32_16x16x32_bf16 v[76:79], v[128:131], v[184:187], 0
	v_mfma_f32_16x16x32_bf16 v[72:75], v[136:139], v[184:187], 0
	v_mfma_f32_16x16x32_bf16 v[124:127], v[132:135], v[164:167], v[124:127]
	v_mfma_f32_16x16x32_bf16 v[120:123], v[140:143], v[164:167], v[120:123]
	v_mfma_f32_16x16x32_bf16 v[108:111], v[132:135], v[172:175], v[108:111]
	v_mfma_f32_16x16x32_bf16 v[104:107], v[140:143], v[172:175], v[104:107]
	v_mfma_f32_16x16x32_bf16 v[92:95], v[132:135], v[180:183], v[92:95]
	v_mfma_f32_16x16x32_bf16 v[88:91], v[140:143], v[180:183], v[88:91]
	v_mfma_f32_16x16x32_bf16 v[76:79], v[132:135], v[188:191], v[76:79]
	v_mfma_f32_16x16x32_bf16 v[72:75], v[140:143], v[188:191], v[72:75]
	v_mfma_f32_16x16x32_bf16 v[116:119], v[144:147], v[160:163], 0
	v_mfma_f32_16x16x32_bf16 v[112:115], v[152:155], v[160:163], 0
	v_mfma_f32_16x16x32_bf16 v[100:103], v[144:147], v[168:171], 0
	v_mfma_f32_16x16x32_bf16 v[96:99], v[152:155], v[168:171], 0
	v_mfma_f32_16x16x32_bf16 v[84:87], v[144:147], v[176:179], 0
	v_mfma_f32_16x16x32_bf16 v[80:83], v[152:155], v[176:179], 0
	v_mfma_f32_16x16x32_bf16 v[68:71], v[144:147], v[184:187], 0
	v_mfma_f32_16x16x32_bf16 v[64:67], v[152:155], v[184:187], 0
	v_mfma_f32_16x16x32_bf16 v[116:119], v[148:151], v[164:167], v[116:119]
	v_mfma_f32_16x16x32_bf16 v[112:115], v[156:159], v[164:167], v[112:115]
	v_mfma_f32_16x16x32_bf16 v[100:103], v[148:151], v[172:175], v[100:103]
	v_mfma_f32_16x16x32_bf16 v[96:99], v[156:159], v[172:175], v[96:99]
	v_mfma_f32_16x16x32_bf16 v[84:87], v[148:151], v[180:183], v[84:87]
	v_mfma_f32_16x16x32_bf16 v[80:83], v[156:159], v[180:183], v[80:83]
	v_mfma_f32_16x16x32_bf16 v[68:71], v[148:151], v[188:191], v[68:71]
	v_mfma_f32_16x16x32_bf16 v[64:67], v[156:159], v[188:191], v[64:67]
	s_barrier
	s_setprio 0
	s_add_i32 s42, s77, s35
	s_mov_b32 m0, s42
	ds_read_b128 v[160:163], v231 offset:16384
	ds_read_b128 v[164:167], v231 offset:17408
	ds_read_b128 v[168:171], v231 offset:18432
	ds_read_b128 v[172:175], v231 offset:19456
	ds_read_b128 v[176:179], v231 offset:20480
	ds_read_b128 v[180:183], v231 offset:21504
	ds_read_b128 v[184:187], v231 offset:22528
	ds_read_b128 v[188:191], v231 offset:23552
	global_load_lds_dwordx4 v194, s[48:49]
	s_add_i32 m0, s42, 0x2000
	s_add_u32 s42, s48, 0x40000
	s_addc_u32 s43, s49, 0
	s_add_i32 s84, s78, s35
	global_load_lds_dwordx4 v198, s[48:49]
	s_mov_b32 m0, s84
	s_nop 0
	global_load_lds_dwordx4 v194, s[42:43]
	s_add_i32 m0, s84, 0x2000
	s_nop 0
	global_load_lds_dwordx4 v198, s[42:43]
	s_mov_b32 m0, s23
	s_nop 0
	global_load_lds_dwordx4 v192, s[50:51]
	s_mov_b32 m0, s56
	s_nop 0
	global_load_lds_dwordx4 v196, s[50:51]
	s_waitcnt vmcnt(8)
	s_waitcnt lgkmcnt(0)
	s_setprio 1
	s_barrier
	v_mfma_f32_16x16x32_bf16 v[60:63], v[128:131], v[160:163], 0
	v_mfma_f32_16x16x32_bf16 v[56:59], v[136:139], v[160:163], 0
	v_mfma_f32_16x16x32_bf16 v[44:47], v[128:131], v[168:171], 0
	v_mfma_f32_16x16x32_bf16 v[40:43], v[136:139], v[168:171], 0
	v_mfma_f32_16x16x32_bf16 v[28:31], v[128:131], v[176:179], 0
	v_mfma_f32_16x16x32_bf16 v[24:27], v[136:139], v[176:179], 0
	v_mfma_f32_16x16x32_bf16 v[12:15], v[128:131], v[184:187], 0
	v_mfma_f32_16x16x32_bf16 v[8:11], v[136:139], v[184:187], 0
	v_mfma_f32_16x16x32_bf16 v[60:63], v[132:135], v[164:167], v[60:63]
	v_mfma_f32_16x16x32_bf16 v[56:59], v[140:143], v[164:167], v[56:59]
	v_mfma_f32_16x16x32_bf16 v[44:47], v[132:135], v[172:175], v[44:47]
	v_mfma_f32_16x16x32_bf16 v[40:43], v[140:143], v[172:175], v[40:43]
	v_mfma_f32_16x16x32_bf16 v[28:31], v[132:135], v[180:183], v[28:31]
	v_mfma_f32_16x16x32_bf16 v[24:27], v[140:143], v[180:183], v[24:27]
	v_mfma_f32_16x16x32_bf16 v[12:15], v[132:135], v[188:191], v[12:15]
	v_mfma_f32_16x16x32_bf16 v[8:11], v[140:143], v[188:191], v[8:11]
	v_mfma_f32_16x16x32_bf16 v[52:55], v[144:147], v[160:163], 0
	v_mfma_f32_16x16x32_bf16 v[48:51], v[152:155], v[160:163], 0
	v_mfma_f32_16x16x32_bf16 v[36:39], v[144:147], v[168:171], 0
	v_mfma_f32_16x16x32_bf16 v[32:35], v[152:155], v[168:171], 0
	v_mfma_f32_16x16x32_bf16 v[20:23], v[144:147], v[176:179], 0
	v_mfma_f32_16x16x32_bf16 v[16:19], v[152:155], v[176:179], 0
	v_mfma_f32_16x16x32_bf16 v[4:7], v[144:147], v[184:187], 0
	v_mfma_f32_16x16x32_bf16 v[0:3], v[152:155], v[184:187], 0
	v_mfma_f32_16x16x32_bf16 v[52:55], v[148:151], v[164:167], v[52:55]
	v_mfma_f32_16x16x32_bf16 v[48:51], v[156:159], v[164:167], v[48:51]
	v_mfma_f32_16x16x32_bf16 v[36:39], v[148:151], v[172:175], v[36:39]
	v_mfma_f32_16x16x32_bf16 v[32:35], v[156:159], v[172:175], v[32:35]
	v_mfma_f32_16x16x32_bf16 v[20:23], v[148:151], v[180:183], v[20:23]
	v_mfma_f32_16x16x32_bf16 v[16:19], v[156:159], v[180:183], v[16:19]
	v_mfma_f32_16x16x32_bf16 v[4:7], v[148:151], v[188:191], v[4:7]
	v_mfma_f32_16x16x32_bf16 v[0:3], v[156:159], v[188:191], v[0:3]
	s_barrier
	s_setprio 0
	s_add_i32 s84, 0, 0x18000
	s_add_i32 s85, 0, 0x1c000
	v_add_u32_e32 v140, s84, v228
	v_add_u32_e32 v156, s85, v228
	ds_read_b128 v[128:131], v140
	ds_read_b128 v[132:135], v140 offset:1024
	ds_read_b128 v[136:139], v140 offset:2048
	ds_read_b128 v[140:143], v140 offset:3072
	ds_read_b128 v[144:147], v156
	ds_read_b128 v[148:151], v156 offset:1024
	ds_read_b128 v[152:155], v156 offset:2048
	ds_read_b128 v[156:159], v156 offset:3072
	s_add_u32 s42, s50, 0x2000
	s_addc_u32 s43, s51, 0
	s_mov_b32 m0, s57
	ds_read_b128 v[160:163], v231 offset:32768
	ds_read_b128 v[164:167], v231 offset:33792
	ds_read_b128 v[168:171], v231 offset:34816
	ds_read_b128 v[172:175], v231 offset:35840
	ds_read_b128 v[176:179], v231 offset:36864
	ds_read_b128 v[180:183], v231 offset:37888
	ds_read_b128 v[184:187], v231 offset:38912
	ds_read_b128 v[188:191], v231 offset:39936
	global_load_lds_dwordx4 v192, s[42:43]
	s_mov_b32 m0, s59
	s_nop 0
	global_load_lds_dwordx4 v196, s[42:43]
	s_waitcnt vmcnt(8)
	s_waitcnt lgkmcnt(0)
	s_setprio 1
	s_barrier
	v_mfma_f32_16x16x32_bf16 v[124:127], v[128:131], v[160:163], v[124:127]
	v_mfma_f32_16x16x32_bf16 v[120:123], v[136:139], v[160:163], v[120:123]
	v_mfma_f32_16x16x32_bf16 v[108:111], v[128:131], v[168:171], v[108:111]
	v_mfma_f32_16x16x32_bf16 v[104:107], v[136:139], v[168:171], v[104:107]
	v_mfma_f32_16x16x32_bf16 v[92:95], v[128:131], v[176:179], v[92:95]
	v_mfma_f32_16x16x32_bf16 v[88:91], v[136:139], v[176:179], v[88:91]
	v_mfma_f32_16x16x32_bf16 v[76:79], v[128:131], v[184:187], v[76:79]
	v_mfma_f32_16x16x32_bf16 v[72:75], v[136:139], v[184:187], v[72:75]
	v_mfma_f32_16x16x32_bf16 v[124:127], v[132:135], v[164:167], v[124:127]
	v_mfma_f32_16x16x32_bf16 v[120:123], v[140:143], v[164:167], v[120:123]
	v_mfma_f32_16x16x32_bf16 v[108:111], v[132:135], v[172:175], v[108:111]
	v_mfma_f32_16x16x32_bf16 v[104:107], v[140:143], v[172:175], v[104:107]
	v_mfma_f32_16x16x32_bf16 v[92:95], v[132:135], v[180:183], v[92:95]
	v_mfma_f32_16x16x32_bf16 v[88:91], v[140:143], v[180:183], v[88:91]
	v_mfma_f32_16x16x32_bf16 v[76:79], v[132:135], v[188:191], v[76:79]
	v_mfma_f32_16x16x32_bf16 v[72:75], v[140:143], v[188:191], v[72:75]
	v_mfma_f32_16x16x32_bf16 v[116:119], v[144:147], v[160:163], v[116:119]
	v_mfma_f32_16x16x32_bf16 v[112:115], v[152:155], v[160:163], v[112:115]
	v_mfma_f32_16x16x32_bf16 v[100:103], v[144:147], v[168:171], v[100:103]
	v_mfma_f32_16x16x32_bf16 v[96:99], v[152:155], v[168:171], v[96:99]
	v_mfma_f32_16x16x32_bf16 v[84:87], v[144:147], v[176:179], v[84:87]
	v_mfma_f32_16x16x32_bf16 v[80:83], v[152:155], v[176:179], v[80:83]
	v_mfma_f32_16x16x32_bf16 v[68:71], v[144:147], v[184:187], v[68:71]
	v_mfma_f32_16x16x32_bf16 v[64:67], v[152:155], v[184:187], v[64:67]
	v_mfma_f32_16x16x32_bf16 v[116:119], v[148:151], v[164:167], v[116:119]
	v_mfma_f32_16x16x32_bf16 v[112:115], v[156:159], v[164:167], v[112:115]
	v_mfma_f32_16x16x32_bf16 v[100:103], v[148:151], v[172:175], v[100:103]
	v_mfma_f32_16x16x32_bf16 v[96:99], v[156:159], v[172:175], v[96:99]
	v_mfma_f32_16x16x32_bf16 v[84:87], v[148:151], v[180:183], v[84:87]
	v_mfma_f32_16x16x32_bf16 v[80:83], v[156:159], v[180:183], v[80:83]
	v_mfma_f32_16x16x32_bf16 v[68:71], v[148:151], v[188:191], v[68:71]
	v_mfma_f32_16x16x32_bf16 v[64:67], v[156:159], v[188:191], v[64:67]
	s_barrier
	s_setprio 0
	s_add_u32 s98, s48, s16
	s_addc_u32 s99, s49, s17
	s_add_i32 s42, s84, s35
	s_mov_b32 m0, s42
	ds_read_b128 v[160:163], v231 offset:49152
	ds_read_b128 v[164:167], v231 offset:50176
	ds_read_b128 v[168:171], v231 offset:51200
	ds_read_b128 v[172:175], v231 offset:52224
	ds_read_b128 v[176:179], v231 offset:53248
	ds_read_b128 v[180:183], v231 offset:54272
	ds_read_b128 v[184:187], v231 offset:55296
	ds_read_b128 v[188:191], v231 offset:56320
	global_load_lds_dwordx4 v194, s[98:99]
	s_add_i32 m0, s42, 0x2000
	s_add_u32 s42, s48, 0x40080
	s_addc_u32 s43, s49, 0
	s_add_i32 s48, s85, s35
	global_load_lds_dwordx4 v198, s[98:99]
	s_mov_b32 m0, s48
	s_nop 0
	global_load_lds_dwordx4 v194, s[42:43]
	s_add_i32 m0, s48, 0x2000
	s_nop 0
	global_load_lds_dwordx4 v198, s[42:43]
	s_mov_b32 m0, s75
	s_nop 0
	global_load_lds_dwordx4 v192, s[46:47]
	s_mov_b32 m0, s76
	s_nop 0
	global_load_lds_dwordx4 v196, s[46:47]
	s_waitcnt vmcnt(8)
	s_waitcnt lgkmcnt(0)
	s_setprio 1
	s_barrier
	v_mfma_f32_16x16x32_bf16 v[60:63], v[128:131], v[160:163], v[60:63]
	v_mfma_f32_16x16x32_bf16 v[56:59], v[136:139], v[160:163], v[56:59]
	v_mfma_f32_16x16x32_bf16 v[44:47], v[128:131], v[168:171], v[44:47]
	v_mfma_f32_16x16x32_bf16 v[40:43], v[136:139], v[168:171], v[40:43]
	v_mfma_f32_16x16x32_bf16 v[28:31], v[128:131], v[176:179], v[28:31]
	v_mfma_f32_16x16x32_bf16 v[24:27], v[136:139], v[176:179], v[24:27]
	v_mfma_f32_16x16x32_bf16 v[12:15], v[128:131], v[184:187], v[12:15]
	v_mfma_f32_16x16x32_bf16 v[8:11], v[136:139], v[184:187], v[8:11]
	v_mfma_f32_16x16x32_bf16 v[60:63], v[132:135], v[164:167], v[60:63]
	v_mfma_f32_16x16x32_bf16 v[56:59], v[140:143], v[164:167], v[56:59]
	v_mfma_f32_16x16x32_bf16 v[44:47], v[132:135], v[172:175], v[44:47]
	v_mfma_f32_16x16x32_bf16 v[40:43], v[140:143], v[172:175], v[40:43]
	v_mfma_f32_16x16x32_bf16 v[28:31], v[132:135], v[180:183], v[28:31]
	v_mfma_f32_16x16x32_bf16 v[24:27], v[140:143], v[180:183], v[24:27]
	v_mfma_f32_16x16x32_bf16 v[12:15], v[132:135], v[188:191], v[12:15]
	v_mfma_f32_16x16x32_bf16 v[8:11], v[140:143], v[188:191], v[8:11]
	v_mfma_f32_16x16x32_bf16 v[52:55], v[144:147], v[160:163], v[52:55]
	v_mfma_f32_16x16x32_bf16 v[48:51], v[152:155], v[160:163], v[48:51]
	v_mfma_f32_16x16x32_bf16 v[36:39], v[144:147], v[168:171], v[36:39]
	v_mfma_f32_16x16x32_bf16 v[32:35], v[152:155], v[168:171], v[32:35]
	v_mfma_f32_16x16x32_bf16 v[20:23], v[144:147], v[176:179], v[20:23]
	v_mfma_f32_16x16x32_bf16 v[16:19], v[152:155], v[176:179], v[16:19]
	v_mfma_f32_16x16x32_bf16 v[4:7], v[144:147], v[184:187], v[4:7]
	v_mfma_f32_16x16x32_bf16 v[0:3], v[152:155], v[184:187], v[0:3]
	v_mfma_f32_16x16x32_bf16 v[52:55], v[148:151], v[164:167], v[52:55]
	v_mfma_f32_16x16x32_bf16 v[48:51], v[156:159], v[164:167], v[48:51]
	v_mfma_f32_16x16x32_bf16 v[36:39], v[148:151], v[172:175], v[36:39]
	v_mfma_f32_16x16x32_bf16 v[32:35], v[156:159], v[172:175], v[32:35]
	v_mfma_f32_16x16x32_bf16 v[20:23], v[148:151], v[180:183], v[20:23]
	v_mfma_f32_16x16x32_bf16 v[16:19], v[156:159], v[180:183], v[16:19]
	v_mfma_f32_16x16x32_bf16 v[4:7], v[148:151], v[188:191], v[4:7]
	v_mfma_f32_16x16x32_bf16 v[0:3], v[156:159], v[188:191], v[0:3]
	s_barrier
	s_setprio 0
	s_add_i32 s83, s83, 2
	s_add_u32 s80, s80, 0x100
	s_addc_u32 s81, s81, 0
	s_cmp_gt_u32 s83, 13
	s_mov_b64 s[42:43], s[44:45]

.LBB0_567:
	s_ashr_i32 s19, s18, 31
	s_lshl_b64 s[20:21], s[18:19], 19
	s_add_u32 s20, s14, s20
	s_addc_u32 s21, s15, s21
	s_and_b64 s[22:23], s[4:5], exec
	s_cselect_b32 s19, s21, s29
	s_cselect_b32 s27, s20, s28
	s_ashr_i32 s17, s16, 31
	s_lshl_b64 s[22:23], s[16:17], 19
	s_add_u32 s22, s33, s22
	s_addc_u32 s23, s34, s23
	s_and_b64 s[38:39], s[4:5], exec
	s_cselect_b32 s17, s23, s37
	s_cselect_b32 s73, s22, s36
	s_add_u32 s74, s36, 0x100
	s_addc_u32 s75, s37, 0
	s_mov_b32 s76, -2
	ds_read_b128 v[128:131], v167
	ds_read_b128 v[132:135], v167 offset:1024
	ds_read_b128 v[136:139], v167 offset:2048
	ds_read_b128 v[140:143], v167 offset:3072
	ds_read_b128 v[160:163], v168
	ds_read_b128 v[170:173], v168 offset:1024
	ds_read_b128 v[174:177], v168 offset:2048
	ds_read_b128 v[178:181], v168 offset:3072
	s_add_u32 s36, s28, 0x10000
	s_addc_u32 s37, s29, 0
	s_cmp_eq_u32 s76, 12
	s_cselect_b32 s42, s27, s36
	s_cselect_b32 s43, s19, s37
	s_cselect_b32 s40, s73, s74
	s_cselect_b32 s41, s17, s75
	s_add_u32 s38, s42, 0x8000
	s_addc_u32 s39, s43, 0
	s_add_i32 m0, s44, 0xc000
	ds_read_b128 v[182:185], v169
	ds_read_b128 v[186:189], v169 offset:1024
	ds_read_b128 v[190:193], v169 offset:2048
	ds_read_b128 v[194:197], v169 offset:3072
	ds_read_b128 v[198:201], v169 offset:4096
	ds_read_b128 v[202:205], v169 offset:5120
	ds_read_b128 v[206:209], v169 offset:6144
	ds_read_b128 v[210:213], v169 offset:7168
	global_load_lds_dwordx4 v152, s[28:29]
	s_add_i32 m0, s44, 0xe000
	s_nop 0
	global_load_lds_dwordx4 v154, s[28:29]
	s_waitcnt vmcnt(8)
	s_waitcnt lgkmcnt(0)
	s_setprio 1
	s_barrier
	v_mfma_f32_16x16x32_bf16 v[124:127], v[128:131], v[182:185], 0
	v_mfma_f32_16x16x32_bf16 v[120:123], v[136:139], v[182:185], 0
	v_mfma_f32_16x16x32_bf16 v[116:119], v[128:131], v[190:193], 0
	v_mfma_f32_16x16x32_bf16 v[112:115], v[136:139], v[190:193], 0
	v_mfma_f32_16x16x32_bf16 v[92:95], v[128:131], v[198:201], 0
	v_mfma_f32_16x16x32_bf16 v[88:91], v[136:139], v[198:201], 0
	v_mfma_f32_16x16x32_bf16 v[76:79], v[128:131], v[206:209], 0
	v_mfma_f32_16x16x32_bf16 v[72:75], v[136:139], v[206:209], 0
	v_mfma_f32_16x16x32_bf16 v[124:127], v[132:135], v[186:189], v[124:127]
	v_mfma_f32_16x16x32_bf16 v[120:123], v[140:143], v[186:189], v[120:123]
	v_mfma_f32_16x16x32_bf16 v[116:119], v[132:135], v[194:197], v[116:119]
	v_mfma_f32_16x16x32_bf16 v[112:115], v[140:143], v[194:197], v[112:115]
	v_mfma_f32_16x16x32_bf16 v[92:95], v[132:135], v[202:205], v[92:95]
	v_mfma_f32_16x16x32_bf16 v[88:91], v[140:143], v[202:205], v[88:91]
	v_mfma_f32_16x16x32_bf16 v[76:79], v[132:135], v[210:213], v[76:79]
	v_mfma_f32_16x16x32_bf16 v[72:75], v[140:143], v[210:213], v[72:75]
	v_mfma_f32_16x16x32_bf16 v[108:111], v[160:163], v[182:185], 0
	v_mfma_f32_16x16x32_bf16 v[104:107], v[174:177], v[182:185], 0
	v_mfma_f32_16x16x32_bf16 v[100:103], v[160:163], v[190:193], 0
	v_mfma_f32_16x16x32_bf16 v[96:99], v[174:177], v[190:193], 0
	v_mfma_f32_16x16x32_bf16 v[84:87], v[160:163], v[198:201], 0
	v_mfma_f32_16x16x32_bf16 v[80:83], v[174:177], v[198:201], 0
	v_mfma_f32_16x16x32_bf16 v[68:71], v[160:163], v[206:209], 0
	v_mfma_f32_16x16x32_bf16 v[64:67], v[174:177], v[206:209], 0
	v_mfma_f32_16x16x32_bf16 v[108:111], v[170:173], v[186:189], v[108:111]
	v_mfma_f32_16x16x32_bf16 v[104:107], v[178:181], v[186:189], v[104:107]
	v_mfma_f32_16x16x32_bf16 v[100:103], v[170:173], v[194:197], v[100:103]
	v_mfma_f32_16x16x32_bf16 v[96:99], v[178:181], v[194:197], v[96:99]
	v_mfma_f32_16x16x32_bf16 v[84:87], v[170:173], v[202:205], v[84:87]
	v_mfma_f32_16x16x32_bf16 v[80:83], v[178:181], v[202:205], v[80:83]
	v_mfma_f32_16x16x32_bf16 v[68:71], v[170:173], v[210:213], v[68:71]
	v_mfma_f32_16x16x32_bf16 v[64:67], v[178:181], v[210:213], v[64:67]
	s_barrier
	s_setprio 0
	s_add_i32 s28, s70, s35
	s_mov_b32 m0, s28
	ds_read_b128 v[182:185], v169 offset:16384
	ds_read_b128 v[186:189], v169 offset:17408
	ds_read_b128 v[190:193], v169 offset:18432
	ds_read_b128 v[194:197], v169 offset:19456
	ds_read_b128 v[198:201], v169 offset:20480
	ds_read_b128 v[202:205], v169 offset:21504
	ds_read_b128 v[206:209], v169 offset:22528
	ds_read_b128 v[210:213], v169 offset:23552
	global_load_lds_dwordx4 v148, s[40:41]
	s_add_i32 m0, s28, 0x2000
	s_add_u32 s28, s40, 0x40000
	s_addc_u32 s29, s41, 0
	s_add_i32 s77, s71, s35
	global_load_lds_dwordx4 v144, s[40:41]
	s_mov_b32 m0, s77
	s_nop 0
	global_load_lds_dwordx4 v148, s[28:29]
	s_add_i32 m0, s77, 0x2000
	s_nop 0
	global_load_lds_dwordx4 v144, s[28:29]
	s_mov_b32 m0, s44
	s_nop 0
	global_load_lds_dwordx4 v150, s[42:43]
	s_mov_b32 m0, s45
	s_nop 0
	global_load_lds_dwordx4 v146, s[42:43]
	s_waitcnt vmcnt(8)
	s_waitcnt lgkmcnt(0)
	s_setprio 1
	s_barrier
	v_mfma_f32_16x16x32_bf16 v[60:63], v[128:131], v[182:185], 0
	v_mfma_f32_16x16x32_bf16 v[56:59], v[136:139], v[182:185], 0
	v_mfma_f32_16x16x32_bf16 v[44:47], v[128:131], v[190:193], 0
	v_mfma_f32_16x16x32_bf16 v[40:43], v[136:139], v[190:193], 0
	v_mfma_f32_16x16x32_bf16 v[28:31], v[128:131], v[198:201], 0
	v_mfma_f32_16x16x32_bf16 v[24:27], v[136:139], v[198:201], 0
	v_mfma_f32_16x16x32_bf16 v[12:15], v[128:131], v[206:209], 0
	v_mfma_f32_16x16x32_bf16 v[8:11], v[136:139], v[206:209], 0
	v_mfma_f32_16x16x32_bf16 v[60:63], v[132:135], v[186:189], v[60:63]
	v_mfma_f32_16x16x32_bf16 v[56:59], v[140:143], v[186:189], v[56:59]
	v_mfma_f32_16x16x32_bf16 v[44:47], v[132:135], v[194:197], v[44:47]
	v_mfma_f32_16x16x32_bf16 v[40:43], v[140:143], v[194:197], v[40:43]
	v_mfma_f32_16x16x32_bf16 v[28:31], v[132:135], v[202:205], v[28:31]
	v_mfma_f32_16x16x32_bf16 v[24:27], v[140:143], v[202:205], v[24:27]
	v_mfma_f32_16x16x32_bf16 v[12:15], v[132:135], v[210:213], v[12:15]
	v_mfma_f32_16x16x32_bf16 v[8:11], v[140:143], v[210:213], v[8:11]
	v_mfma_f32_16x16x32_bf16 v[52:55], v[160:163], v[182:185], 0
	v_mfma_f32_16x16x32_bf16 v[48:51], v[174:177], v[182:185], 0
	v_mfma_f32_16x16x32_bf16 v[36:39], v[160:163], v[190:193], 0
	v_mfma_f32_16x16x32_bf16 v[32:35], v[174:177], v[190:193], 0
	v_mfma_f32_16x16x32_bf16 v[20:23], v[160:163], v[198:201], 0
	v_mfma_f32_16x16x32_bf16 v[16:19], v[174:177], v[198:201], 0
	v_mfma_f32_16x16x32_bf16 v[4:7], v[160:163], v[206:209], 0
	v_mfma_f32_16x16x32_bf16 v[0:3], v[174:177], v[206:209], 0
	v_mfma_f32_16x16x32_bf16 v[52:55], v[170:173], v[186:189], v[52:55]
	v_mfma_f32_16x16x32_bf16 v[48:51], v[178:181], v[186:189], v[48:51]
	v_mfma_f32_16x16x32_bf16 v[36:39], v[170:173], v[194:197], v[36:39]
	v_mfma_f32_16x16x32_bf16 v[32:35], v[178:181], v[194:197], v[32:35]
	v_mfma_f32_16x16x32_bf16 v[20:23], v[170:173], v[202:205], v[20:23]
	v_mfma_f32_16x16x32_bf16 v[16:19], v[178:181], v[202:205], v[16:19]
	v_mfma_f32_16x16x32_bf16 v[4:7], v[170:173], v[210:213], v[4:7]
	v_mfma_f32_16x16x32_bf16 v[0:3], v[178:181], v[210:213], v[0:3]
	s_barrier
	s_setprio 0
	s_add_i32 s77, 0, 0x18000
	s_add_i32 s78, 0, 0x1c000
	v_add_u32_e32 v140, s77, v166
	v_add_u32_e32 v178, s78, v166
	ds_read_b128 v[128:131], v140
	ds_read_b128 v[132:135], v140 offset:1024
	ds_read_b128 v[136:139], v140 offset:2048
	ds_read_b128 v[140:143], v140 offset:3072
	ds_read_b128 v[160:163], v178
	ds_read_b128 v[170:173], v178 offset:1024
	ds_read_b128 v[174:177], v178 offset:2048
	ds_read_b128 v[178:181], v178 offset:3072
	s_add_u32 s28, s42, 0x2000
	s_addc_u32 s29, s43, 0
	s_mov_b32 m0, s46
	ds_read_b128 v[182:185], v169 offset:32768
	ds_read_b128 v[186:189], v169 offset:33792
	ds_read_b128 v[190:193], v169 offset:34816
	ds_read_b128 v[194:197], v169 offset:35840
	ds_read_b128 v[198:201], v169 offset:36864
	ds_read_b128 v[202:205], v169 offset:37888
	ds_read_b128 v[206:209], v169 offset:38912
	ds_read_b128 v[210:213], v169 offset:39936
	global_load_lds_dwordx4 v150, s[28:29]
	s_mov_b32 m0, s47
	s_nop 0
	global_load_lds_dwordx4 v146, s[28:29]
	s_waitcnt vmcnt(8)
	s_waitcnt lgkmcnt(0)
	s_setprio 1
	s_barrier
	v_mfma_f32_16x16x32_bf16 v[124:127], v[128:131], v[182:185], v[124:127]
	v_mfma_f32_16x16x32_bf16 v[120:123], v[136:139], v[182:185], v[120:123]
	v_mfma_f32_16x16x32_bf16 v[116:119], v[128:131], v[190:193], v[116:119]
	v_mfma_f32_16x16x32_bf16 v[112:115], v[136:139], v[190:193], v[112:115]
	v_mfma_f32_16x16x32_bf16 v[92:95], v[128:131], v[198:201], v[92:95]
	v_mfma_f32_16x16x32_bf16 v[88:91], v[136:139], v[198:201], v[88:91]
	v_mfma_f32_16x16x32_bf16 v[76:79], v[128:131], v[206:209], v[76:79]
	v_mfma_f32_16x16x32_bf16 v[72:75], v[136:139], v[206:209], v[72:75]
	v_mfma_f32_16x16x32_bf16 v[124:127], v[132:135], v[186:189], v[124:127]
	v_mfma_f32_16x16x32_bf16 v[120:123], v[140:143], v[186:189], v[120:123]
	v_mfma_f32_16x16x32_bf16 v[116:119], v[132:135], v[194:197], v[116:119]
	v_mfma_f32_16x16x32_bf16 v[112:115], v[140:143], v[194:197], v[112:115]
	v_mfma_f32_16x16x32_bf16 v[92:95], v[132:135], v[202:205], v[92:95]
	v_mfma_f32_16x16x32_bf16 v[88:91], v[140:143], v[202:205], v[88:91]
	v_mfma_f32_16x16x32_bf16 v[76:79], v[132:135], v[210:213], v[76:79]
	v_mfma_f32_16x16x32_bf16 v[72:75], v[140:143], v[210:213], v[72:75]
	v_mfma_f32_16x16x32_bf16 v[108:111], v[160:163], v[182:185], v[108:111]
	v_mfma_f32_16x16x32_bf16 v[104:107], v[174:177], v[182:185], v[104:107]
	v_mfma_f32_16x16x32_bf16 v[100:103], v[160:163], v[190:193], v[100:103]
	v_mfma_f32_16x16x32_bf16 v[96:99], v[174:177], v[190:193], v[96:99]
	v_mfma_f32_16x16x32_bf16 v[84:87], v[160:163], v[198:201], v[84:87]
	v_mfma_f32_16x16x32_bf16 v[80:83], v[174:177], v[198:201], v[80:83]
	v_mfma_f32_16x16x32_bf16 v[68:71], v[160:163], v[206:209], v[68:71]
	v_mfma_f32_16x16x32_bf16 v[64:67], v[174:177], v[206:209], v[64:67]
	v_mfma_f32_16x16x32_bf16 v[108:111], v[170:173], v[186:189], v[108:111]
	v_mfma_f32_16x16x32_bf16 v[104:107], v[178:181], v[186:189], v[104:107]
	v_mfma_f32_16x16x32_bf16 v[100:103], v[170:173], v[194:197], v[100:103]
	v_mfma_f32_16x16x32_bf16 v[96:99], v[178:181], v[194:197], v[96:99]
	v_mfma_f32_16x16x32_bf16 v[84:87], v[170:173], v[202:205], v[84:87]
	v_mfma_f32_16x16x32_bf16 v[80:83], v[178:181], v[202:205], v[80:83]
	v_mfma_f32_16x16x32_bf16 v[68:71], v[170:173], v[210:213], v[68:71]
	v_mfma_f32_16x16x32_bf16 v[64:67], v[178:181], v[210:213], v[64:67]
	s_barrier
	s_setprio 0
	s_add_u32 s98, s40, s12
	s_addc_u32 s99, s41, s13
	s_add_i32 s28, s77, s35
	s_mov_b32 m0, s28
	ds_read_b128 v[182:185], v169 offset:49152
	ds_read_b128 v[186:189], v169 offset:50176
	ds_read_b128 v[190:193], v169 offset:51200
	ds_read_b128 v[194:197], v169 offset:52224
	ds_read_b128 v[198:201], v169 offset:53248
	ds_read_b128 v[202:205], v169 offset:54272
	ds_read_b128 v[206:209], v169 offset:55296
	ds_read_b128 v[210:213], v169 offset:56320
	global_load_lds_dwordx4 v148, s[98:99]
	s_add_i32 m0, s28, 0x2000
	s_add_u32 s28, s40, 0x40080
	s_addc_u32 s29, s41, 0
	s_add_i32 s40, s78, s35
	global_load_lds_dwordx4 v144, s[98:99]
	s_mov_b32 m0, s40
	s_nop 0
	global_load_lds_dwordx4 v148, s[28:29]
	s_add_i32 m0, s40, 0x2000
	s_nop 0
	global_load_lds_dwordx4 v144, s[28:29]
	s_mov_b32 m0, s68
	s_nop 0
	global_load_lds_dwordx4 v150, s[38:39]
	s_mov_b32 m0, s69
	s_nop 0
	global_load_lds_dwordx4 v146, s[38:39]
	s_waitcnt vmcnt(8)
	s_waitcnt lgkmcnt(0)
	s_setprio 1
	s_barrier
	v_mfma_f32_16x16x32_bf16 v[60:63], v[128:131], v[182:185], v[60:63]
	v_mfma_f32_16x16x32_bf16 v[56:59], v[136:139], v[182:185], v[56:59]
	v_mfma_f32_16x16x32_bf16 v[44:47], v[128:131], v[190:193], v[44:47]
	v_mfma_f32_16x16x32_bf16 v[40:43], v[136:139], v[190:193], v[40:43]
	v_mfma_f32_16x16x32_bf16 v[28:31], v[128:131], v[198:201], v[28:31]
	v_mfma_f32_16x16x32_bf16 v[24:27], v[136:139], v[198:201], v[24:27]
	v_mfma_f32_16x16x32_bf16 v[12:15], v[128:131], v[206:209], v[12:15]
	v_mfma_f32_16x16x32_bf16 v[8:11], v[136:139], v[206:209], v[8:11]
	v_mfma_f32_16x16x32_bf16 v[60:63], v[132:135], v[186:189], v[60:63]
	v_mfma_f32_16x16x32_bf16 v[56:59], v[140:143], v[186:189], v[56:59]
	v_mfma_f32_16x16x32_bf16 v[44:47], v[132:135], v[194:197], v[44:47]
	v_mfma_f32_16x16x32_bf16 v[40:43], v[140:143], v[194:197], v[40:43]
	v_mfma_f32_16x16x32_bf16 v[28:31], v[132:135], v[202:205], v[28:31]
	v_mfma_f32_16x16x32_bf16 v[24:27], v[140:143], v[202:205], v[24:27]
	v_mfma_f32_16x16x32_bf16 v[12:15], v[132:135], v[210:213], v[12:15]
	v_mfma_f32_16x16x32_bf16 v[8:11], v[140:143], v[210:213], v[8:11]
	v_mfma_f32_16x16x32_bf16 v[52:55], v[160:163], v[182:185], v[52:55]
	v_mfma_f32_16x16x32_bf16 v[48:51], v[174:177], v[182:185], v[48:51]
	v_mfma_f32_16x16x32_bf16 v[36:39], v[160:163], v[190:193], v[36:39]
	v_mfma_f32_16x16x32_bf16 v[32:35], v[174:177], v[190:193], v[32:35]
	v_mfma_f32_16x16x32_bf16 v[20:23], v[160:163], v[198:201], v[20:23]
	v_mfma_f32_16x16x32_bf16 v[16:19], v[174:177], v[198:201], v[16:19]
	v_mfma_f32_16x16x32_bf16 v[4:7], v[160:163], v[206:209], v[4:7]
	v_mfma_f32_16x16x32_bf16 v[0:3], v[174:177], v[206:209], v[0:3]
	v_mfma_f32_16x16x32_bf16 v[52:55], v[170:173], v[186:189], v[52:55]
	v_mfma_f32_16x16x32_bf16 v[48:51], v[178:181], v[186:189], v[48:51]
	v_mfma_f32_16x16x32_bf16 v[36:39], v[170:173], v[194:197], v[36:39]
	v_mfma_f32_16x16x32_bf16 v[32:35], v[178:181], v[194:197], v[32:35]
	v_mfma_f32_16x16x32_bf16 v[20:23], v[170:173], v[202:205], v[20:23]
	v_mfma_f32_16x16x32_bf16 v[16:19], v[178:181], v[202:205], v[16:19]
	v_mfma_f32_16x16x32_bf16 v[4:7], v[170:173], v[210:213], v[4:7]
	v_mfma_f32_16x16x32_bf16 v[0:3], v[178:181], v[210:213], v[0:3]
	s_barrier
	s_setprio 0
	s_add_i32 s76, s76, 2
	s_add_u32 s74, s74, 0x100
	s_addc_u32 s75, s75, 0
	s_cmp_gt_u32 s76, 13
	s_mov_b64 s[28:29], s[36:37]
